# SwiGLU GEMM: LDS tile image re-laid so each LDS-DMA covers 8 whole 128-B lines (XOR-swizzled, conflict-free reads), DMA loads with sc1 (L1 bypass)
# speedup vs baseline: 1.0011x; 1.0011x over previous
.LBB0_202:
	s_cmpk_gt_i32 s0, 0x15ff
	v_mbcnt_lo_u32_b32 v14, -1, 0
	v_mbcnt_hi_u32_b32 v14, -1, v14
	s_cbranch_scc1 .LBB0_220
	s_mul_i32 s58, s52, 0x1600000
	s_lshl_b64 s[12:13], s[58:59], 1
	s_add_u32 s2, s10, s12
	s_addc_u32 s12, s11, s13
	s_add_u32 s2, s2, 0x4000000
	s_addc_u32 s40, s12, 0
	s_lshl_b32 s41, s1, 10
	v_lshl_add_u32 v1, v14, 4, s41
	v_add_u32_e32 v0, 0x2000, v1
	v_ashrrev_i32_e32 v2, 31, v0
	v_lshrrev_b32_e32 v2, 22, v2
	v_add_u32_e32 v2, v0, v2
	v_ashrrev_i32_e32 v12, 10, v2
	v_mul_i32_i24_e32 v2, 0x400, v12
	v_sub_u32_e32 v0, v0, v2
	v_lshrrev_b32_e32 v2, 4, v0
	v_bitop3_b32 v0, v2, v0, 32 bitop3:0x6c
	v_ashrrev_i32_e32 v2, 31, v0
	v_lshrrev_b32_e32 v2, 26, v2
	v_add_u32_e32 v2, v0, v2
	v_ashrrev_i32_e32 v13, 6, v2
	v_lshlrev_b32_e32 v4, 3, v12
	v_and_b32_e32 v2, 0xffc0, v2
	v_and_b32_e32 v4, -16, v4
	v_sub_u32_e32 v0, v0, v2
	v_add_u32_e32 v4, v13, v4
	v_lshrrev_b16_e32 v2, 7, v0
	v_and_b32_e32 v5, 3, v13
	s_mov_b32 s12, 0xfffe0
	v_lshrrev_b32_e32 v6, 2, v4
	v_lshlrev_b32_e32 v7, 1, v4
	v_and_b32_e32 v2, 1, v2
	v_and_or_b32 v5, v4, s12, v5
	v_and_b32_e32 v6, 4, v6
	v_and_b32_e32 v7, 24, v7
	v_add_u16_e32 v0, v0, v2
	v_mov_b32_e32 v8, 1
	v_or3_b32 v5, v5, v6, v7
	v_lshlrev_b32_e32 v6, 5, v12
	v_ashrrev_i16_sdwa v0, v8, sext(v0) dst_sel:DWORD dst_unused:UNUSED_PAD src0_sel:DWORD src1_sel:BYTE_0
	v_and_b32_e32 v6, 32, v6
	v_bfe_i32 v15, v0, 0, 16
	v_add_lshl_u32 v2, v6, v15, 1
	v_lshl_add_u32 v0, v5, 12, v2
	v_lshl_add_u32 v132, v4, 12, v2
	v_ashrrev_i32_e32 v2, 31, v1
	v_lshrrev_b32_e32 v2, 22, v2
	v_add_u32_e32 v2, v1, v2
	v_ashrrev_i32_e32 v16, 10, v2
	v_mul_i32_i24_e32 v2, 0x400, v16
	v_sub_u32_e32 v1, v1, v2
	v_lshrrev_b32_e32 v2, 4, v1
	v_bitop3_b32 v1, v2, v1, 32 bitop3:0x6c
	v_ashrrev_i32_e32 v2, 31, v1
	v_lshrrev_b32_e32 v2, 26, v2
	v_add_u32_e32 v2, v1, v2
	v_lshlrev_b32_e32 v4, 3, v16
	v_ashrrev_i32_e32 v17, 6, v2
	v_and_b32_e32 v4, -16, v4
	v_add_u32_e32 v4, v17, v4
	v_and_b32_e32 v5, 3, v17
	s_ashr_i32 s42, s0, 31
	v_and_or_b32 v5, v4, s12, v5
	s_lshr_b32 s12, s42, 29
	s_add_i32 s12, s0, s12
	s_ashr_i32 s13, s12, 3
	s_and_b32 s12, s12, -8
	s_ashr_i32 s18, s1, 2
	s_sub_i32 s12, s0, s12
	s_cmp_lt_i32 s12, 0
	s_movk_i32 s14, 0x2c1
	s_cselect_b32 s14, s14, 0x2c0
	s_mul_i32 s12, s12, s14
	s_add_i32 s12, s12, s13
	s_mul_hi_i32 s13, s12, 0x2e8ba2e9
	s_lshr_b32 s14, s13, 31
	s_ashr_i32 s13, s13, 5
	s_add_i32 s13, s13, s14
	s_lshl_b32 s14, s13, 2
	s_mulk_i32 s13, 0xb0
	s_sub_i32 s12, s12, s13
	s_bfe_u32 s13, s12, 0x2001d
	s_add_i32 s13, s12, s13
	s_sext_i32_i16 s15, s13
	s_and_b32 s13, s13, 0xfffc
	s_sub_i32 s12, s12, s13
	s_sext_i32_i16 s12, s12
	v_lshrrev_b32_e32 v6, 2, v4
	v_lshlrev_b32_e32 v7, 1, v4
	v_and_b32_e32 v2, 0xc0, v2
	s_lshr_b32 s16, s15, 2
	s_add_i32 s26, s14, s12
	v_and_b32_e32 v6, 4, v6
	v_and_b32_e32 v7, 24, v7
	v_sub_u32_e32 v1, v1, v2
	s_ashr_i32 s27, s26, 31
	s_bfe_i64 s[14:15], s[16:17], 0x100000
	v_or3_b32 v5, v5, v6, v7
	v_lshlrev_b32_e32 v6, 5, v16
	v_ashrrev_i16_sdwa v1, v8, sext(v1) dst_sel:DWORD dst_unused:UNUSED_PAD src0_sel:DWORD src1_sel:BYTE_0
	s_lshl_b64 s[12:13], s[26:27], 20
	s_lshl_b64 s[14:15], s[14:15], 20
	v_and_b32_e32 v6, 32, v6
	v_bfe_i32 v18, v1, 0, 16
	s_add_u32 s30, s2, s14
	v_add_lshl_u32 v1, v6, v18, 1
	s_addc_u32 s31, s40, s15
	s_add_i32 s43, s41, 0
	v_lshl_add_u32 v2, v5, 12, v1
	s_add_i32 m0, s43, 0x10000
	v_lshl_add_u32 v134, v4, 12, v1
	v_readlane_b32 s98, v253, 9
	v_mbcnt_lo_u32_b32 v249, -1, 0
	v_mbcnt_hi_u32_b32 v249, -1, v249
	v_lshrrev_b32_e32 v250, 3, v249
	v_and_b32_e32 v251, 7, v249
	v_xor_b32_e32 v251, v251, v250
	v_lshlrev_b32_e32 v251, 4, v251
	v_mov_b32_e32 v235, s98
	v_lshl_add_u32 v236, v235, 3, v250
	v_lshl_add_u32 v134, v236, 12, v251
	v_add_u32_e32 v132, 0x40000, v134
	v_lshrrev_b32_e32 v236, 2, v235
	v_lshlrev_b32_e32 v236, 5, v236
	v_and_b32_e32 v237, 1, v235
	v_lshl_add_u32 v236, v237, 4, v236
	v_bfe_u32 v237, v235, 1, 1
	v_lshl_add_u32 v236, v237, 2, v236
	v_lshrrev_b32_e32 v237, 2, v250
	v_lshl_add_u32 v236, v237, 3, v236
	v_and_b32_e32 v237, 3, v250
	v_add_u32_e32 v236, v236, v237
	v_lshl_add_u32 v2, v236, 12, v251
	v_add_u32_e32 v0, 0x40000, v2
	global_load_lds_dwordx4 v2, s[30:31] sc1
	s_add_i32 m0, s43, 0x12000
	s_add_u32 s14, s30, 0x80000
	global_load_lds_dwordx4 v0, s[30:31] sc1
	s_addc_u32 s15, s31, 0
	s_add_i32 m0, s43, 0x14000
	v_mov_b32_e32 v1, v3
	global_load_lds_dwordx4 v2, s[14:15] sc1
	s_add_i32 m0, s43, 0x16000
	s_add_u32 s28, s4, s12
	s_addc_u32 s29, s5, s13
	s_add_i32 s44, s43, 0x2000
	global_load_lds_dwordx4 v0, s[14:15] sc1
	s_mov_b32 m0, s43
	s_add_u32 s12, s28, 0x80000
	global_load_lds_dwordx4 v134, s[28:29] sc1
	s_mov_b32 m0, s44
	s_addc_u32 s13, s29, 0
	s_add_i32 s45, s43, 0x4000
	global_load_lds_dwordx4 v132, s[28:29] sc1
	s_mov_b32 m0, s45
	s_add_i32 s47, s43, 0x6000
	global_load_lds_dwordx4 v134, s[12:13] sc1
	s_mov_b32 m0, s47
	v_mov_b32_e32 v135, v3
	global_load_lds_dwordx4 v132, s[12:13] sc1
	v_mov_b32_e32 v133, v3
	s_cmp_eq_u32 s18, 1
	v_mov_b32_e32 v252, 1
	v_lshl_add_u64 v[10:11], s[30:31], 0, v[2:3]
	v_lshl_add_u64 v[8:9], s[30:31], 0, v[0:1]
	v_lshl_add_u64 v[4:5], s[28:29], 0, v[134:135]
	s_cselect_b64 s[12:13], -1, 0
	s_cmp_lg_u32 s18, 1
	v_lshl_add_u64 v[6:7], s[28:29], 0, v[132:133]
	s_cbranch_scc1 .LBB0_205
	s_barrier
.LBB0_205:
	s_lshl_b32 s14, s46, 17
	v_readlane_b32 s20, v254, 46
	s_add_i32 s58, s14, s20
	v_readlane_b32 s21, v254, 47
	s_add_u32 s14, s10, 0x35800000
	s_addc_u32 s15, s11, 0
	s_lshl_b64 s[20:21], s[58:59], 2
	s_add_u32 s10, s10, s20
	s_addc_u32 s11, s11, s21
	s_add_u32 s10, s10, 0x62800000
	s_addc_u32 s11, s11, 0
	s_and_b32 s19, s1, 3
	s_add_i32 m0, s43, 0x18000
	v_lshl_add_u64 v[10:11], v[10:11], 0, s[66:67]
	s_lshl_b32 s46, s18, 6
	s_lshl_b32 s17, s18, 13
	s_lshl_b32 s22, s19, 12
	s_waitcnt vmcnt(2)
	s_barrier
	global_load_lds_dwordx4 v[10:11], off sc1
	v_lshl_add_u64 v[8:9], v[8:9], 0, s[66:67]
	s_add_i32 m0, s43, 0x1a000
	s_add_i32 s48, s43, 0x8000
	s_add_i32 s49, s43, 0xa000
	global_load_lds_dwordx4 v[8:9], off sc1
	v_lshl_add_u64 v[4:5], v[4:5], 0, s[66:67]
	s_mov_b32 m0, s48
	s_add_u32 s20, s30, 0x80080
	global_load_lds_dwordx4 v[4:5], off sc1
	v_lshl_add_u64 v[4:5], v[6:7], 0, s[66:67]
	s_mov_b32 m0, s49
	s_addc_u32 s21, s31, 0
	global_load_lds_dwordx4 v[4:5], off sc1
	s_add_i32 m0, s43, 0x1c000
	v_lshl_add_u64 v[4:5], s[20:21], 0, v[2:3]
	global_load_lds_dwordx4 v[4:5], off sc1
	v_lshl_add_u64 v[4:5], s[20:21], 0, v[0:1]
	s_add_i32 m0, s43, 0x1e000
	s_cmp_lt_u32 s1, 4
	global_load_lds_dwordx4 v[4:5], off sc1
	v_lshrrev_b32_e32 v5, 1, v14
	v_and_b32_e32 v5, 24, v5
	v_and_b32_e32 v4, 15, v14
	v_lshlrev_b32_e32 v6, 1, v5
	s_waitcnt vmcnt(0)
	v_or_b32_e32 v150, s46, v4
	v_lshl_or_b32 v6, v4, 6, v6
	v_lshlrev_b32_e32 v4, 2, v4
	v_and_b32_e32 v7, 32, v4
	s_sext_i32_i16 s27, s16
	v_bitop3_b32 v8, v6, s17, v7 bitop3:0xde
	s_cselect_b64 s[16:17], -1, 0
	s_lshl_b32 s1, s18, 11
	s_add_i32 s1, s1, 0
	s_lshl_b32 s18, s19, 9
	s_add_i32 s1, s1, s18
	s_add_i32 s1, s1, 0x20400
	s_waitcnt lgkmcnt(0)
	v_add_u32_e32 v152, s1, v4
	v_lshlrev_b32_e32 v4, 15, v16
	v_and_b32_e32 v4, 0xffff0000, v4
	v_lshl_or_b32 v153, s19, 5, v5
	v_lshl_add_u32 v4, v17, 12, v4
	v_and_b32_e32 v5, 1, v16
	v_lshl_or_b32 v4, v5, 6, v4
	v_lshl_add_u32 v136, v18, 1, v4
	v_lshlrev_b32_e32 v4, 15, v12
	v_and_b32_e32 v4, 0xffff0000, v4
	s_waitcnt vmcnt(6)
	v_lshl_add_u32 v4, v13, 12, v4
	v_and_b32_e32 v5, 1, v12
	v_lshl_or_b32 v4, v5, 6, v4
	v_bitop3_b32 v151, v6, s22, v7 bitop3:0xde
	v_mov_b32_e32 v137, v3
	v_lshl_add_u32 v138, v15, 1, v4
	v_mov_b32_e32 v139, v3
	s_mov_b32 s50, 0
	s_mov_b32 s51, -1
	v_add_u32_e32 v154, 0, v8
	v_readlane_b32 s98, v253, 9
	v_mbcnt_lo_u32_b32 v249, -1, 0
	v_mbcnt_hi_u32_b32 v249, -1, v249
	v_and_b32_e32 v250, 15, v249
	v_lshrrev_b32_e32 v251, 4, v249
	v_and_b32_e32 v235, 7, v250
	v_lshrrev_b32_e32 v236, 3, v250
	v_lshlrev_b32_e32 v236, 10, v236
	v_lshl_add_u32 v236, v235, 7, v236
	v_xor_b32_e32 v237, v251, v235
	v_lshl_add_u32 v238, v237, 4, v236
	v_xor_b32_e32 v237, 4, v237
	v_lshl_add_u32 v239, v237, 4, v236
	v_mov_b32_e32 v240, s98
	v_lshrrev_b32_e32 v241, 2, v240
	v_lshlrev_b32_e32 v241, 13, v241
	v_add_u32_e32 v154, v241, v238
	v_add_u32_e32 v247, v241, v239
	v_and_b32_e32 v241, 3, v240
	v_lshlrev_b32_e32 v241, 12, v241
	v_add_u32_e32 v151, v241, v238
	v_add_u32_e32 v248, v241, v239
	v_mov_b32_e32 v136, v134
	v_mov_b32_e32 v138, v132
	s_barrier
	s_branch .LBB0_208

.LBB0_210:
	s_ashr_i32 s21, s20, 31
	s_lshl_b64 s[22:23], s[20:21], 20
	s_add_u32 s22, s4, s22
	s_addc_u32 s23, s5, s23
	s_and_b64 s[24:25], s[34:35], exec
	s_cselect_b32 s21, s23, s29
	s_cselect_b32 s53, s22, s28
	s_ashr_i32 s19, s18, 31
	s_lshl_b64 s[24:25], s[18:19], 20
	s_add_u32 s24, s2, s24
	s_addc_u32 s25, s40, s25
	s_and_b64 s[38:39], s[34:35], exec
	s_cselect_b32 s19, s25, s31
	s_cselect_b32 s54, s24, s30
	s_add_u32 s28, s28, 0x80080
	s_addc_u32 s29, s29, 0
	s_add_u32 s55, s30, 0x100
	s_addc_u32 s56, s31, 0
	s_mov_b32 s57, -2
	s_sleep 2
	s_add_u32 s30, s28, 0xfff80080
	s_addc_u32 s31, s29, -1
	s_add_i32 s58, 0, 0x10000
	s_cmp_eq_u32 s57, 28
	s_cselect_b32 s39, s21, s31
	s_cselect_b32 s38, s53, s30
	v_add_u32_e32 v148, s58, v151
	v_add_u32_e32 v249, s58, v248
	s_cselect_b32 s31, s19, s56
	s_cselect_b32 s30, s54, s55
	s_add_i32 s60, 0, 0x14000
	ds_read_b128 v[140:143], v148
	ds_read_b128 v[144:147], v249 offset:0
	ds_read_b128 v[156:159], v148 offset:2048
	ds_read_b128 v[160:163], v249 offset:2048
	v_add_u32_e32 v148, s60, v151
	v_add_u32_e32 v249, s60, v248
	ds_read_b128 v[164:167], v148
	ds_read_b128 v[168:171], v249 offset:0
	ds_read_b128 v[172:175], v148 offset:2048
	ds_read_b128 v[176:179], v249 offset:2048
	s_add_i32 m0, s43, 0xc000
	ds_read_b128 v[180:183], v154
	ds_read_b128 v[184:187], v247 offset:0
	ds_read_b128 v[188:191], v154 offset:2048
	ds_read_b128 v[192:195], v247 offset:2048
	ds_read_b128 v[196:199], v154 offset:4096
	ds_read_b128 v[200:203], v247 offset:4096
	ds_read_b128 v[208:211], v154 offset:6144
	ds_read_b128 v[212:215], v247 offset:6144
	global_load_lds_dwordx4 v136, s[28:29] sc1
	s_add_i32 m0, s43, 0xe000
	s_nop 0
	global_load_lds_dwordx4 v138, s[28:29] sc1
	s_waitcnt vmcnt(8)
	s_waitcnt lgkmcnt(0)
	s_barrier
	s_setprio 1
	s_waitcnt lgkmcnt(0)
	v_mfma_f32_16x16x32_bf16 v[128:131], v[140:143], v[180:183], 0
	v_mfma_f32_16x16x32_bf16 v[128:131], v[144:147], v[184:187], v[128:131]
	v_mfma_f32_16x16x32_bf16 v[120:123], v[164:167], v[180:183], 0
	v_mfma_f32_16x16x32_bf16 v[120:123], v[168:171], v[184:187], v[120:123]
	v_mfma_f32_16x16x32_bf16 v[124:127], v[156:159], v[180:183], 0
	v_mfma_f32_16x16x32_bf16 v[124:127], v[160:163], v[184:187], v[124:127]
	v_mfma_f32_16x16x32_bf16 v[116:119], v[172:175], v[180:183], 0
	v_mfma_f32_16x16x32_bf16 v[116:119], v[176:179], v[184:187], v[116:119]
	v_mfma_f32_16x16x32_bf16 v[112:115], v[140:143], v[188:191], 0
	v_mfma_f32_16x16x32_bf16 v[112:115], v[144:147], v[192:195], v[112:115]
	v_mfma_f32_16x16x32_bf16 v[104:107], v[164:167], v[188:191], 0
	v_mfma_f32_16x16x32_bf16 v[104:107], v[168:171], v[192:195], v[104:107]
	v_mfma_f32_16x16x32_bf16 v[108:111], v[156:159], v[188:191], 0
	v_mfma_f32_16x16x32_bf16 v[108:111], v[160:163], v[192:195], v[108:111]
	v_mfma_f32_16x16x32_bf16 v[100:103], v[172:175], v[188:191], 0
	v_mfma_f32_16x16x32_bf16 v[100:103], v[176:179], v[192:195], v[100:103]
	v_mfma_f32_16x16x32_bf16 v[96:99], v[140:143], v[196:199], 0
	v_mfma_f32_16x16x32_bf16 v[96:99], v[144:147], v[200:203], v[96:99]
	v_mfma_f32_16x16x32_bf16 v[88:91], v[164:167], v[196:199], 0
	v_mfma_f32_16x16x32_bf16 v[88:91], v[168:171], v[200:203], v[88:91]
	v_mfma_f32_16x16x32_bf16 v[92:95], v[156:159], v[196:199], 0
	v_mfma_f32_16x16x32_bf16 v[92:95], v[160:163], v[200:203], v[92:95]
	v_mfma_f32_16x16x32_bf16 v[84:87], v[172:175], v[196:199], 0
	v_mfma_f32_16x16x32_bf16 v[84:87], v[176:179], v[200:203], v[84:87]
	v_mfma_f32_16x16x32_bf16 v[80:83], v[140:143], v[208:211], 0
	v_mfma_f32_16x16x32_bf16 v[80:83], v[144:147], v[212:215], v[80:83]
	v_mfma_f32_16x16x32_bf16 v[72:75], v[164:167], v[208:211], 0
	v_mfma_f32_16x16x32_bf16 v[72:75], v[168:171], v[212:215], v[72:75]
	v_mfma_f32_16x16x32_bf16 v[76:79], v[156:159], v[208:211], 0
	v_mfma_f32_16x16x32_bf16 v[76:79], v[160:163], v[212:215], v[76:79]
	v_mfma_f32_16x16x32_bf16 v[68:71], v[172:175], v[208:211], 0
	v_mfma_f32_16x16x32_bf16 v[68:71], v[176:179], v[212:215], v[68:71]
	s_setprio 0
	s_barrier
	s_sleep 2
	s_add_i32 s58, s58, s41
	s_mov_b32 m0, s58
	ds_read_b128 v[180:183], v154 offset:16384
	ds_read_b128 v[184:187], v247 offset:16384
	ds_read_b128 v[188:191], v154 offset:18432
	ds_read_b128 v[192:195], v247 offset:18432
	ds_read_b128 v[196:199], v154 offset:20480
	ds_read_b128 v[200:203], v247 offset:20480
	ds_read_b128 v[208:211], v154 offset:22528
	ds_read_b128 v[212:215], v247 offset:22528
	global_load_lds_dwordx4 v2, s[30:31] sc1
	s_add_i32 m0, s58, 0x2000
	s_add_u32 s62, s30, 0x80000
	s_addc_u32 s63, s31, 0
	s_add_i32 s58, s60, s41
	global_load_lds_dwordx4 v0, s[30:31] sc1
	s_mov_b32 m0, s58
	s_nop 0
	global_load_lds_dwordx4 v2, s[62:63] sc1
	s_add_i32 m0, s58, 0x2000
	s_nop 0
	global_load_lds_dwordx4 v0, s[62:63] sc1
	s_mov_b32 m0, s43
	s_nop 0
	global_load_lds_dwordx4 v134, s[38:39] sc1
	s_mov_b32 m0, s44
	s_nop 0
	global_load_lds_dwordx4 v132, s[38:39] sc1
	s_waitcnt vmcnt(8)
	s_waitcnt lgkmcnt(0)
	s_barrier
	s_setprio 1
	s_waitcnt lgkmcnt(0)
	v_mfma_f32_16x16x32_bf16 v[64:67], v[140:143], v[180:183], 0
	v_mfma_f32_16x16x32_bf16 v[64:67], v[144:147], v[184:187], v[64:67]
	v_mfma_f32_16x16x32_bf16 v[56:59], v[164:167], v[180:183], 0
	v_mfma_f32_16x16x32_bf16 v[56:59], v[168:171], v[184:187], v[56:59]
	v_mfma_f32_16x16x32_bf16 v[60:63], v[156:159], v[180:183], 0
	v_mfma_f32_16x16x32_bf16 v[60:63], v[160:163], v[184:187], v[60:63]
	v_mfma_f32_16x16x32_bf16 v[52:55], v[172:175], v[180:183], 0
	v_mfma_f32_16x16x32_bf16 v[52:55], v[176:179], v[184:187], v[52:55]
	v_mfma_f32_16x16x32_bf16 v[48:51], v[140:143], v[188:191], 0
	v_mfma_f32_16x16x32_bf16 v[48:51], v[144:147], v[192:195], v[48:51]
	v_mfma_f32_16x16x32_bf16 v[40:43], v[164:167], v[188:191], 0
	v_mfma_f32_16x16x32_bf16 v[40:43], v[168:171], v[192:195], v[40:43]
	v_mfma_f32_16x16x32_bf16 v[44:47], v[156:159], v[188:191], 0
	v_mfma_f32_16x16x32_bf16 v[44:47], v[160:163], v[192:195], v[44:47]
	v_mfma_f32_16x16x32_bf16 v[36:39], v[172:175], v[188:191], 0
	v_mfma_f32_16x16x32_bf16 v[36:39], v[176:179], v[192:195], v[36:39]
	v_mfma_f32_16x16x32_bf16 v[32:35], v[140:143], v[196:199], 0
	v_mfma_f32_16x16x32_bf16 v[32:35], v[144:147], v[200:203], v[32:35]
	v_mfma_f32_16x16x32_bf16 v[24:27], v[164:167], v[196:199], 0
	v_mfma_f32_16x16x32_bf16 v[24:27], v[168:171], v[200:203], v[24:27]
	v_mfma_f32_16x16x32_bf16 v[28:31], v[156:159], v[196:199], 0
	v_mfma_f32_16x16x32_bf16 v[28:31], v[160:163], v[200:203], v[28:31]
	v_mfma_f32_16x16x32_bf16 v[20:23], v[172:175], v[196:199], 0
	v_mfma_f32_16x16x32_bf16 v[20:23], v[176:179], v[200:203], v[20:23]
	v_mfma_f32_16x16x32_bf16 v[16:19], v[140:143], v[208:211], 0
	v_mfma_f32_16x16x32_bf16 v[16:19], v[144:147], v[212:215], v[16:19]
	v_mfma_f32_16x16x32_bf16 v[8:11], v[164:167], v[208:211], 0
	v_mfma_f32_16x16x32_bf16 v[8:11], v[168:171], v[212:215], v[8:11]
	v_mfma_f32_16x16x32_bf16 v[12:15], v[156:159], v[208:211], 0
	v_mfma_f32_16x16x32_bf16 v[12:15], v[160:163], v[212:215], v[12:15]
	v_mfma_f32_16x16x32_bf16 v[4:7], v[172:175], v[208:211], 0
	v_mfma_f32_16x16x32_bf16 v[4:7], v[176:179], v[212:215], v[4:7]
	s_setprio 0
	s_barrier
	s_sleep 2
	s_add_i32 s58, 0, 0x18000
	v_add_u32_e32 v155, s58, v151
	v_add_u32_e32 v249, s58, v248
	s_add_i32 s60, 0, 0x1c000
	ds_read_b128 v[140:143], v155
	ds_read_b128 v[144:147], v249 offset:0
	ds_read_b128 v[156:159], v155 offset:2048
	ds_read_b128 v[160:163], v249 offset:2048
	v_add_u32_e32 v155, s60, v151
	v_add_u32_e32 v249, s60, v248
	ds_read_b128 v[164:167], v155
	ds_read_b128 v[168:171], v249 offset:0
	ds_read_b128 v[172:175], v155 offset:2048
	ds_read_b128 v[176:179], v249 offset:2048
	s_add_u32 s38, s38, 0x80000
	s_addc_u32 s39, s39, 0
	s_mov_b32 m0, s45
	ds_read_b128 v[180:183], v154 offset:32768
	ds_read_b128 v[184:187], v247 offset:32768
	ds_read_b128 v[188:191], v154 offset:34816
	ds_read_b128 v[192:195], v247 offset:34816
	ds_read_b128 v[196:199], v154 offset:36864
	ds_read_b128 v[200:203], v247 offset:36864
	ds_read_b128 v[208:211], v154 offset:38912
	ds_read_b128 v[212:215], v247 offset:38912
	global_load_lds_dwordx4 v134, s[38:39] sc1
	s_mov_b32 m0, s47
	s_nop 0
	global_load_lds_dwordx4 v132, s[38:39] sc1
	s_waitcnt vmcnt(8)
	s_waitcnt lgkmcnt(0)
	s_barrier
	s_setprio 1
	s_waitcnt lgkmcnt(0)
	v_mfma_f32_16x16x32_bf16 v[128:131], v[140:143], v[180:183], v[128:131]
	v_mfma_f32_16x16x32_bf16 v[128:131], v[144:147], v[184:187], v[128:131]
	v_mfma_f32_16x16x32_bf16 v[120:123], v[164:167], v[180:183], v[120:123]
	v_mfma_f32_16x16x32_bf16 v[120:123], v[168:171], v[184:187], v[120:123]
	v_mfma_f32_16x16x32_bf16 v[124:127], v[156:159], v[180:183], v[124:127]
	v_mfma_f32_16x16x32_bf16 v[124:127], v[160:163], v[184:187], v[124:127]
	v_mfma_f32_16x16x32_bf16 v[116:119], v[172:175], v[180:183], v[116:119]
	v_mfma_f32_16x16x32_bf16 v[116:119], v[176:179], v[184:187], v[116:119]
	v_mfma_f32_16x16x32_bf16 v[112:115], v[140:143], v[188:191], v[112:115]
	v_mfma_f32_16x16x32_bf16 v[112:115], v[144:147], v[192:195], v[112:115]
	v_mfma_f32_16x16x32_bf16 v[104:107], v[164:167], v[188:191], v[104:107]
	v_mfma_f32_16x16x32_bf16 v[104:107], v[168:171], v[192:195], v[104:107]
	v_mfma_f32_16x16x32_bf16 v[108:111], v[156:159], v[188:191], v[108:111]
	v_mfma_f32_16x16x32_bf16 v[108:111], v[160:163], v[192:195], v[108:111]
	v_mfma_f32_16x16x32_bf16 v[100:103], v[172:175], v[188:191], v[100:103]
	v_mfma_f32_16x16x32_bf16 v[100:103], v[176:179], v[192:195], v[100:103]
	v_mfma_f32_16x16x32_bf16 v[96:99], v[140:143], v[196:199], v[96:99]
	v_mfma_f32_16x16x32_bf16 v[96:99], v[144:147], v[200:203], v[96:99]
	v_mfma_f32_16x16x32_bf16 v[88:91], v[164:167], v[196:199], v[88:91]
	v_mfma_f32_16x16x32_bf16 v[88:91], v[168:171], v[200:203], v[88:91]
	v_mfma_f32_16x16x32_bf16 v[92:95], v[156:159], v[196:199], v[92:95]
	v_mfma_f32_16x16x32_bf16 v[92:95], v[160:163], v[200:203], v[92:95]
	v_mfma_f32_16x16x32_bf16 v[84:87], v[172:175], v[196:199], v[84:87]
	v_mfma_f32_16x16x32_bf16 v[84:87], v[176:179], v[200:203], v[84:87]
	v_mfma_f32_16x16x32_bf16 v[80:83], v[140:143], v[208:211], v[80:83]
	v_mfma_f32_16x16x32_bf16 v[80:83], v[144:147], v[212:215], v[80:83]
	v_mfma_f32_16x16x32_bf16 v[72:75], v[164:167], v[208:211], v[72:75]
	v_mfma_f32_16x16x32_bf16 v[72:75], v[168:171], v[212:215], v[72:75]
	v_mfma_f32_16x16x32_bf16 v[76:79], v[156:159], v[208:211], v[76:79]
	v_mfma_f32_16x16x32_bf16 v[76:79], v[160:163], v[212:215], v[76:79]
	v_mfma_f32_16x16x32_bf16 v[68:71], v[172:175], v[208:211], v[68:71]
	v_mfma_f32_16x16x32_bf16 v[68:71], v[176:179], v[212:215], v[68:71]
	s_setprio 0
	s_barrier
	s_sleep 2
	s_add_i32 s62, s58, s41
	s_add_u32 s30, s30, 0x80
	s_addc_u32 s31, s31, 0
	s_mov_b32 m0, s62
	ds_read_b128 v[180:183], v154 offset:49152
	ds_read_b128 v[184:187], v247 offset:49152
	ds_read_b128 v[188:191], v154 offset:51200
	ds_read_b128 v[192:195], v247 offset:51200
	ds_read_b128 v[196:199], v154 offset:53248
	ds_read_b128 v[200:203], v247 offset:53248
	ds_read_b128 v[208:211], v154 offset:55296
	ds_read_b128 v[212:215], v247 offset:55296
	global_load_lds_dwordx4 v2, s[30:31] sc1
	s_add_i32 m0, s62, 0x2000
	s_nop 0
	s_add_i32 s62, s60, s41
	global_load_lds_dwordx4 v0, s[30:31] sc1
	s_add_u32 s30, s30, 0x80000
	s_addc_u32 s31, s31, 0
	s_mov_b32 m0, s62
	s_nop 0
	global_load_lds_dwordx4 v2, s[30:31] sc1
	s_add_i32 m0, s62, 0x2000
	s_nop 0
	global_load_lds_dwordx4 v0, s[30:31] sc1
	s_sub_u32 s38, s38, 0x7ff80
	s_subb_u32 s39, s39, 0
	s_mov_b32 m0, s48
	s_nop 0
	global_load_lds_dwordx4 v134, s[38:39] sc1
	s_mov_b32 m0, s49
	s_nop 0
	global_load_lds_dwordx4 v132, s[38:39] sc1
	s_waitcnt vmcnt(8)
	s_waitcnt lgkmcnt(0)
	s_barrier
	s_setprio 1
	s_waitcnt lgkmcnt(0)
	v_mfma_f32_16x16x32_bf16 v[64:67], v[140:143], v[180:183], v[64:67]
	v_mfma_f32_16x16x32_bf16 v[64:67], v[144:147], v[184:187], v[64:67]
	v_mfma_f32_16x16x32_bf16 v[56:59], v[164:167], v[180:183], v[56:59]
	v_mfma_f32_16x16x32_bf16 v[56:59], v[168:171], v[184:187], v[56:59]
	v_mfma_f32_16x16x32_bf16 v[60:63], v[156:159], v[180:183], v[60:63]
	v_mfma_f32_16x16x32_bf16 v[60:63], v[160:163], v[184:187], v[60:63]
	v_mfma_f32_16x16x32_bf16 v[52:55], v[172:175], v[180:183], v[52:55]
	v_mfma_f32_16x16x32_bf16 v[52:55], v[176:179], v[184:187], v[52:55]
	v_mfma_f32_16x16x32_bf16 v[48:51], v[140:143], v[188:191], v[48:51]
	v_mfma_f32_16x16x32_bf16 v[48:51], v[144:147], v[192:195], v[48:51]
	v_mfma_f32_16x16x32_bf16 v[40:43], v[164:167], v[188:191], v[40:43]
	v_mfma_f32_16x16x32_bf16 v[40:43], v[168:171], v[192:195], v[40:43]
	v_mfma_f32_16x16x32_bf16 v[44:47], v[156:159], v[188:191], v[44:47]
	v_mfma_f32_16x16x32_bf16 v[44:47], v[160:163], v[192:195], v[44:47]
	v_mfma_f32_16x16x32_bf16 v[36:39], v[172:175], v[188:191], v[36:39]
	v_mfma_f32_16x16x32_bf16 v[36:39], v[176:179], v[192:195], v[36:39]
	v_mfma_f32_16x16x32_bf16 v[32:35], v[140:143], v[196:199], v[32:35]
	v_mfma_f32_16x16x32_bf16 v[32:35], v[144:147], v[200:203], v[32:35]
	v_mfma_f32_16x16x32_bf16 v[24:27], v[164:167], v[196:199], v[24:27]
	v_mfma_f32_16x16x32_bf16 v[24:27], v[168:171], v[200:203], v[24:27]
	v_mfma_f32_16x16x32_bf16 v[28:31], v[156:159], v[196:199], v[28:31]
	v_mfma_f32_16x16x32_bf16 v[28:31], v[160:163], v[200:203], v[28:31]
	v_mfma_f32_16x16x32_bf16 v[20:23], v[172:175], v[196:199], v[20:23]
	v_mfma_f32_16x16x32_bf16 v[20:23], v[176:179], v[200:203], v[20:23]
	v_mfma_f32_16x16x32_bf16 v[16:19], v[140:143], v[208:211], v[16:19]
	v_mfma_f32_16x16x32_bf16 v[16:19], v[144:147], v[212:215], v[16:19]
	v_mfma_f32_16x16x32_bf16 v[8:11], v[164:167], v[208:211], v[8:11]
	v_mfma_f32_16x16x32_bf16 v[8:11], v[168:171], v[212:215], v[8:11]
	v_mfma_f32_16x16x32_bf16 v[12:15], v[156:159], v[208:211], v[12:15]
	v_mfma_f32_16x16x32_bf16 v[12:15], v[160:163], v[212:215], v[12:15]
	v_mfma_f32_16x16x32_bf16 v[4:7], v[172:175], v[208:211], v[4:7]
	v_mfma_f32_16x16x32_bf16 v[4:7], v[176:179], v[212:215], v[4:7]
	s_setprio 0
	s_barrier
	s_add_i32 s57, s57, 2
	s_add_u32 s28, s28, 0x100
	s_addc_u32 s29, s29, 0
	s_add_u32 s55, s55, 0x100
	s_addc_u32 s56, s56, 0
	s_cmp_gt_u32 s57, 29
.LBB0_211:
	s_sleep 2
	s_add_u32 s30, s28, 0xfff80080
	s_addc_u32 s31, s29, -1
	s_add_i32 s58, 0, 0x10000
	s_cmp_eq_u32 s57, 28
	s_cselect_b32 s39, s21, s31
	s_cselect_b32 s38, s53, s30
	v_add_u32_e32 v148, s58, v151
	v_add_u32_e32 v249, s58, v248
	s_cselect_b32 s31, s19, s56
	s_cselect_b32 s30, s54, s55
	s_add_i32 s60, 0, 0x14000
	ds_read_b128 v[140:143], v148
	ds_read_b128 v[144:147], v249 offset:0
	ds_read_b128 v[156:159], v148 offset:2048
	ds_read_b128 v[160:163], v249 offset:2048
	v_add_u32_e32 v148, s60, v151
	v_add_u32_e32 v249, s60, v248
	ds_read_b128 v[164:167], v148
	ds_read_b128 v[168:171], v249 offset:0
	ds_read_b128 v[172:175], v148 offset:2048
	ds_read_b128 v[176:179], v249 offset:2048
	s_add_i32 m0, s43, 0xc000
	ds_read_b128 v[180:183], v154
	ds_read_b128 v[184:187], v247 offset:0
	ds_read_b128 v[188:191], v154 offset:2048
	ds_read_b128 v[192:195], v247 offset:2048
	ds_read_b128 v[196:199], v154 offset:4096
	ds_read_b128 v[200:203], v247 offset:4096
	ds_read_b128 v[208:211], v154 offset:6144
	ds_read_b128 v[212:215], v247 offset:6144
	global_load_lds_dwordx4 v136, s[28:29] sc1
	s_add_i32 m0, s43, 0xe000
	s_nop 0
	global_load_lds_dwordx4 v138, s[28:29] sc1
	s_waitcnt vmcnt(8)
	s_waitcnt lgkmcnt(0)
	s_barrier
	s_setprio 1
	s_waitcnt lgkmcnt(0)
	v_mfma_f32_16x16x32_bf16 v[128:131], v[140:143], v[180:183], v[128:131]
	v_mfma_f32_16x16x32_bf16 v[128:131], v[144:147], v[184:187], v[128:131]
	v_mfma_f32_16x16x32_bf16 v[120:123], v[164:167], v[180:183], v[120:123]
	v_mfma_f32_16x16x32_bf16 v[120:123], v[168:171], v[184:187], v[120:123]
	v_mfma_f32_16x16x32_bf16 v[124:127], v[156:159], v[180:183], v[124:127]
	v_mfma_f32_16x16x32_bf16 v[124:127], v[160:163], v[184:187], v[124:127]
	v_mfma_f32_16x16x32_bf16 v[116:119], v[172:175], v[180:183], v[116:119]
	v_mfma_f32_16x16x32_bf16 v[116:119], v[176:179], v[184:187], v[116:119]
	v_mfma_f32_16x16x32_bf16 v[112:115], v[140:143], v[188:191], v[112:115]
	v_mfma_f32_16x16x32_bf16 v[112:115], v[144:147], v[192:195], v[112:115]
	v_mfma_f32_16x16x32_bf16 v[104:107], v[164:167], v[188:191], v[104:107]
	v_mfma_f32_16x16x32_bf16 v[104:107], v[168:171], v[192:195], v[104:107]
	v_mfma_f32_16x16x32_bf16 v[108:111], v[156:159], v[188:191], v[108:111]
	v_mfma_f32_16x16x32_bf16 v[108:111], v[160:163], v[192:195], v[108:111]
	v_mfma_f32_16x16x32_bf16 v[100:103], v[172:175], v[188:191], v[100:103]
	v_mfma_f32_16x16x32_bf16 v[100:103], v[176:179], v[192:195], v[100:103]
	v_mfma_f32_16x16x32_bf16 v[96:99], v[140:143], v[196:199], v[96:99]
	v_mfma_f32_16x16x32_bf16 v[96:99], v[144:147], v[200:203], v[96:99]
	v_mfma_f32_16x16x32_bf16 v[88:91], v[164:167], v[196:199], v[88:91]
	v_mfma_f32_16x16x32_bf16 v[88:91], v[168:171], v[200:203], v[88:91]
	v_mfma_f32_16x16x32_bf16 v[92:95], v[156:159], v[196:199], v[92:95]
	v_mfma_f32_16x16x32_bf16 v[92:95], v[160:163], v[200:203], v[92:95]
	v_mfma_f32_16x16x32_bf16 v[84:87], v[172:175], v[196:199], v[84:87]
	v_mfma_f32_16x16x32_bf16 v[84:87], v[176:179], v[200:203], v[84:87]
	v_mfma_f32_16x16x32_bf16 v[80:83], v[140:143], v[208:211], v[80:83]
	v_mfma_f32_16x16x32_bf16 v[80:83], v[144:147], v[212:215], v[80:83]
	v_mfma_f32_16x16x32_bf16 v[72:75], v[164:167], v[208:211], v[72:75]
	v_mfma_f32_16x16x32_bf16 v[72:75], v[168:171], v[212:215], v[72:75]
	v_mfma_f32_16x16x32_bf16 v[76:79], v[156:159], v[208:211], v[76:79]
	v_mfma_f32_16x16x32_bf16 v[76:79], v[160:163], v[212:215], v[76:79]
	v_mfma_f32_16x16x32_bf16 v[68:71], v[172:175], v[208:211], v[68:71]
	v_mfma_f32_16x16x32_bf16 v[68:71], v[176:179], v[212:215], v[68:71]
	s_setprio 0
	s_barrier
	s_sleep 2
	s_add_i32 s58, s58, s41
	s_mov_b32 m0, s58
	ds_read_b128 v[180:183], v154 offset:16384
	ds_read_b128 v[184:187], v247 offset:16384
	ds_read_b128 v[188:191], v154 offset:18432
	ds_read_b128 v[192:195], v247 offset:18432
	ds_read_b128 v[196:199], v154 offset:20480
	ds_read_b128 v[200:203], v247 offset:20480
	ds_read_b128 v[208:211], v154 offset:22528
	ds_read_b128 v[212:215], v247 offset:22528
	global_load_lds_dwordx4 v2, s[30:31] sc1
	s_add_i32 m0, s58, 0x2000
	s_add_u32 s62, s30, 0x80000
	s_addc_u32 s63, s31, 0
	s_add_i32 s58, s60, s41
	global_load_lds_dwordx4 v0, s[30:31] sc1
	s_mov_b32 m0, s58
	s_nop 0
	global_load_lds_dwordx4 v2, s[62:63] sc1
	s_add_i32 m0, s58, 0x2000
	s_nop 0
	global_load_lds_dwordx4 v0, s[62:63] sc1
	s_mov_b32 m0, s43
	s_nop 0
	global_load_lds_dwordx4 v134, s[38:39] sc1
	s_mov_b32 m0, s44
	s_nop 0
	global_load_lds_dwordx4 v132, s[38:39] sc1
	s_waitcnt vmcnt(8)
	s_waitcnt lgkmcnt(0)
	s_barrier
	s_setprio 1
	s_waitcnt lgkmcnt(0)
	v_mfma_f32_16x16x32_bf16 v[64:67], v[140:143], v[180:183], v[64:67]
	v_mfma_f32_16x16x32_bf16 v[64:67], v[144:147], v[184:187], v[64:67]
	v_mfma_f32_16x16x32_bf16 v[56:59], v[164:167], v[180:183], v[56:59]
	v_mfma_f32_16x16x32_bf16 v[56:59], v[168:171], v[184:187], v[56:59]
	v_mfma_f32_16x16x32_bf16 v[60:63], v[156:159], v[180:183], v[60:63]
	v_mfma_f32_16x16x32_bf16 v[60:63], v[160:163], v[184:187], v[60:63]
	v_mfma_f32_16x16x32_bf16 v[52:55], v[172:175], v[180:183], v[52:55]
	v_mfma_f32_16x16x32_bf16 v[52:55], v[176:179], v[184:187], v[52:55]
	v_mfma_f32_16x16x32_bf16 v[48:51], v[140:143], v[188:191], v[48:51]
	v_mfma_f32_16x16x32_bf16 v[48:51], v[144:147], v[192:195], v[48:51]
	v_mfma_f32_16x16x32_bf16 v[40:43], v[164:167], v[188:191], v[40:43]
	v_mfma_f32_16x16x32_bf16 v[40:43], v[168:171], v[192:195], v[40:43]
	v_mfma_f32_16x16x32_bf16 v[44:47], v[156:159], v[188:191], v[44:47]
	v_mfma_f32_16x16x32_bf16 v[44:47], v[160:163], v[192:195], v[44:47]
	v_mfma_f32_16x16x32_bf16 v[36:39], v[172:175], v[188:191], v[36:39]
	v_mfma_f32_16x16x32_bf16 v[36:39], v[176:179], v[192:195], v[36:39]
	v_mfma_f32_16x16x32_bf16 v[32:35], v[140:143], v[196:199], v[32:35]
	v_mfma_f32_16x16x32_bf16 v[32:35], v[144:147], v[200:203], v[32:35]
	v_mfma_f32_16x16x32_bf16 v[24:27], v[164:167], v[196:199], v[24:27]
	v_mfma_f32_16x16x32_bf16 v[24:27], v[168:171], v[200:203], v[24:27]
	v_mfma_f32_16x16x32_bf16 v[28:31], v[156:159], v[196:199], v[28:31]
	v_mfma_f32_16x16x32_bf16 v[28:31], v[160:163], v[200:203], v[28:31]
	v_mfma_f32_16x16x32_bf16 v[20:23], v[172:175], v[196:199], v[20:23]
	v_mfma_f32_16x16x32_bf16 v[20:23], v[176:179], v[200:203], v[20:23]
	v_mfma_f32_16x16x32_bf16 v[16:19], v[140:143], v[208:211], v[16:19]
	v_mfma_f32_16x16x32_bf16 v[16:19], v[144:147], v[212:215], v[16:19]
	v_mfma_f32_16x16x32_bf16 v[8:11], v[164:167], v[208:211], v[8:11]
	v_mfma_f32_16x16x32_bf16 v[8:11], v[168:171], v[212:215], v[8:11]
	v_mfma_f32_16x16x32_bf16 v[12:15], v[156:159], v[208:211], v[12:15]
	v_mfma_f32_16x16x32_bf16 v[12:15], v[160:163], v[212:215], v[12:15]
	v_mfma_f32_16x16x32_bf16 v[4:7], v[172:175], v[208:211], v[4:7]
	v_mfma_f32_16x16x32_bf16 v[4:7], v[176:179], v[212:215], v[4:7]
	s_setprio 0
	s_barrier
	s_sleep 2
	s_add_i32 s58, 0, 0x18000
	v_add_u32_e32 v155, s58, v151
	v_add_u32_e32 v249, s58, v248
	s_add_i32 s60, 0, 0x1c000
	ds_read_b128 v[140:143], v155
	ds_read_b128 v[144:147], v249 offset:0
	ds_read_b128 v[156:159], v155 offset:2048
	ds_read_b128 v[160:163], v249 offset:2048
	v_add_u32_e32 v155, s60, v151
	v_add_u32_e32 v249, s60, v248
	ds_read_b128 v[164:167], v155
	ds_read_b128 v[168:171], v249 offset:0
	ds_read_b128 v[172:175], v155 offset:2048
	ds_read_b128 v[176:179], v249 offset:2048
	s_add_u32 s38, s38, 0x80000
	s_addc_u32 s39, s39, 0
	s_mov_b32 m0, s45
	ds_read_b128 v[180:183], v154 offset:32768
	ds_read_b128 v[184:187], v247 offset:32768
	ds_read_b128 v[188:191], v154 offset:34816
	ds_read_b128 v[192:195], v247 offset:34816
	ds_read_b128 v[196:199], v154 offset:36864
	ds_read_b128 v[200:203], v247 offset:36864
	ds_read_b128 v[208:211], v154 offset:38912
	ds_read_b128 v[212:215], v247 offset:38912
	global_load_lds_dwordx4 v134, s[38:39] sc1
	s_mov_b32 m0, s47
	s_nop 0
	global_load_lds_dwordx4 v132, s[38:39] sc1
	s_waitcnt vmcnt(8)
	s_waitcnt lgkmcnt(0)
	s_barrier
	s_setprio 1
	s_waitcnt lgkmcnt(0)
	v_mfma_f32_16x16x32_bf16 v[128:131], v[140:143], v[180:183], v[128:131]
	v_mfma_f32_16x16x32_bf16 v[128:131], v[144:147], v[184:187], v[128:131]
	v_mfma_f32_16x16x32_bf16 v[120:123], v[164:167], v[180:183], v[120:123]
	v_mfma_f32_16x16x32_bf16 v[120:123], v[168:171], v[184:187], v[120:123]
	v_mfma_f32_16x16x32_bf16 v[124:127], v[156:159], v[180:183], v[124:127]
	v_mfma_f32_16x16x32_bf16 v[124:127], v[160:163], v[184:187], v[124:127]
	v_mfma_f32_16x16x32_bf16 v[116:119], v[172:175], v[180:183], v[116:119]
	v_mfma_f32_16x16x32_bf16 v[116:119], v[176:179], v[184:187], v[116:119]
	v_mfma_f32_16x16x32_bf16 v[112:115], v[140:143], v[188:191], v[112:115]
	v_mfma_f32_16x16x32_bf16 v[112:115], v[144:147], v[192:195], v[112:115]
	v_mfma_f32_16x16x32_bf16 v[104:107], v[164:167], v[188:191], v[104:107]
	v_mfma_f32_16x16x32_bf16 v[104:107], v[168:171], v[192:195], v[104:107]
	v_mfma_f32_16x16x32_bf16 v[108:111], v[156:159], v[188:191], v[108:111]
	v_mfma_f32_16x16x32_bf16 v[108:111], v[160:163], v[192:195], v[108:111]
	v_mfma_f32_16x16x32_bf16 v[100:103], v[172:175], v[188:191], v[100:103]
	v_mfma_f32_16x16x32_bf16 v[100:103], v[176:179], v[192:195], v[100:103]
	v_mfma_f32_16x16x32_bf16 v[96:99], v[140:143], v[196:199], v[96:99]
	v_mfma_f32_16x16x32_bf16 v[96:99], v[144:147], v[200:203], v[96:99]
	v_mfma_f32_16x16x32_bf16 v[88:91], v[164:167], v[196:199], v[88:91]
	v_mfma_f32_16x16x32_bf16 v[88:91], v[168:171], v[200:203], v[88:91]
	v_mfma_f32_16x16x32_bf16 v[92:95], v[156:159], v[196:199], v[92:95]
	v_mfma_f32_16x16x32_bf16 v[92:95], v[160:163], v[200:203], v[92:95]
	v_mfma_f32_16x16x32_bf16 v[84:87], v[172:175], v[196:199], v[84:87]
	v_mfma_f32_16x16x32_bf16 v[84:87], v[176:179], v[200:203], v[84:87]
	v_mfma_f32_16x16x32_bf16 v[80:83], v[140:143], v[208:211], v[80:83]
	v_mfma_f32_16x16x32_bf16 v[80:83], v[144:147], v[212:215], v[80:83]
	v_mfma_f32_16x16x32_bf16 v[72:75], v[164:167], v[208:211], v[72:75]
	v_mfma_f32_16x16x32_bf16 v[72:75], v[168:171], v[212:215], v[72:75]
	v_mfma_f32_16x16x32_bf16 v[76:79], v[156:159], v[208:211], v[76:79]
	v_mfma_f32_16x16x32_bf16 v[76:79], v[160:163], v[212:215], v[76:79]
	v_mfma_f32_16x16x32_bf16 v[68:71], v[172:175], v[208:211], v[68:71]
	v_mfma_f32_16x16x32_bf16 v[68:71], v[176:179], v[212:215], v[68:71]
	s_setprio 0
	s_barrier
	s_sleep 2
	s_add_i32 s62, s58, s41
	s_add_u32 s30, s30, 0x80
	s_addc_u32 s31, s31, 0
	s_mov_b32 m0, s62
	ds_read_b128 v[180:183], v154 offset:49152
	ds_read_b128 v[184:187], v247 offset:49152
	ds_read_b128 v[188:191], v154 offset:51200
	ds_read_b128 v[192:195], v247 offset:51200
	ds_read_b128 v[196:199], v154 offset:53248
	ds_read_b128 v[200:203], v247 offset:53248
	ds_read_b128 v[208:211], v154 offset:55296
	ds_read_b128 v[212:215], v247 offset:55296
	global_load_lds_dwordx4 v2, s[30:31] sc1
	s_add_i32 m0, s62, 0x2000
	s_nop 0
	s_add_i32 s62, s60, s41
	global_load_lds_dwordx4 v0, s[30:31] sc1
	s_add_u32 s30, s30, 0x80000
	s_addc_u32 s31, s31, 0
	s_mov_b32 m0, s62
	s_nop 0
	global_load_lds_dwordx4 v2, s[30:31] sc1
	s_add_i32 m0, s62, 0x2000
	s_nop 0
	global_load_lds_dwordx4 v0, s[30:31] sc1
	s_sub_u32 s38, s38, 0x7ff80
	s_subb_u32 s39, s39, 0
	s_mov_b32 m0, s48
	s_nop 0
	global_load_lds_dwordx4 v134, s[38:39] sc1
	s_mov_b32 m0, s49
	s_nop 0
	global_load_lds_dwordx4 v132, s[38:39] sc1
	s_waitcnt vmcnt(8)
	s_waitcnt lgkmcnt(0)
	s_barrier
	s_setprio 1
	s_waitcnt lgkmcnt(0)
	v_mfma_f32_16x16x32_bf16 v[64:67], v[140:143], v[180:183], v[64:67]
	v_mfma_f32_16x16x32_bf16 v[64:67], v[144:147], v[184:187], v[64:67]
	v_mfma_f32_16x16x32_bf16 v[56:59], v[164:167], v[180:183], v[56:59]
	v_mfma_f32_16x16x32_bf16 v[56:59], v[168:171], v[184:187], v[56:59]
	v_mfma_f32_16x16x32_bf16 v[60:63], v[156:159], v[180:183], v[60:63]
	v_mfma_f32_16x16x32_bf16 v[60:63], v[160:163], v[184:187], v[60:63]
	v_mfma_f32_16x16x32_bf16 v[52:55], v[172:175], v[180:183], v[52:55]
	v_mfma_f32_16x16x32_bf16 v[52:55], v[176:179], v[184:187], v[52:55]
	v_mfma_f32_16x16x32_bf16 v[48:51], v[140:143], v[188:191], v[48:51]
	v_mfma_f32_16x16x32_bf16 v[48:51], v[144:147], v[192:195], v[48:51]
	v_mfma_f32_16x16x32_bf16 v[40:43], v[164:167], v[188:191], v[40:43]
	v_mfma_f32_16x16x32_bf16 v[40:43], v[168:171], v[192:195], v[40:43]
	v_mfma_f32_16x16x32_bf16 v[44:47], v[156:159], v[188:191], v[44:47]
	v_mfma_f32_16x16x32_bf16 v[44:47], v[160:163], v[192:195], v[44:47]
	v_mfma_f32_16x16x32_bf16 v[36:39], v[172:175], v[188:191], v[36:39]
	v_mfma_f32_16x16x32_bf16 v[36:39], v[176:179], v[192:195], v[36:39]
	v_mfma_f32_16x16x32_bf16 v[32:35], v[140:143], v[196:199], v[32:35]
	v_mfma_f32_16x16x32_bf16 v[32:35], v[144:147], v[200:203], v[32:35]
	v_mfma_f32_16x16x32_bf16 v[24:27], v[164:167], v[196:199], v[24:27]
	v_mfma_f32_16x16x32_bf16 v[24:27], v[168:171], v[200:203], v[24:27]
	v_mfma_f32_16x16x32_bf16 v[28:31], v[156:159], v[196:199], v[28:31]
	v_mfma_f32_16x16x32_bf16 v[28:31], v[160:163], v[200:203], v[28:31]
	v_mfma_f32_16x16x32_bf16 v[20:23], v[172:175], v[196:199], v[20:23]
	v_mfma_f32_16x16x32_bf16 v[20:23], v[176:179], v[200:203], v[20:23]
	v_mfma_f32_16x16x32_bf16 v[16:19], v[140:143], v[208:211], v[16:19]
	v_mfma_f32_16x16x32_bf16 v[16:19], v[144:147], v[212:215], v[16:19]
	v_mfma_f32_16x16x32_bf16 v[8:11], v[164:167], v[208:211], v[8:11]
	v_mfma_f32_16x16x32_bf16 v[8:11], v[168:171], v[212:215], v[8:11]
	v_mfma_f32_16x16x32_bf16 v[12:15], v[156:159], v[208:211], v[12:15]
	v_mfma_f32_16x16x32_bf16 v[12:15], v[160:163], v[212:215], v[12:15]
	v_mfma_f32_16x16x32_bf16 v[4:7], v[172:175], v[208:211], v[4:7]
	v_mfma_f32_16x16x32_bf16 v[4:7], v[176:179], v[212:215], v[4:7]
	s_setprio 0
	s_barrier
	s_add_i32 s57, s57, 2
	s_add_u32 s28, s28, 0x100
	s_addc_u32 s29, s29, 0
	s_add_u32 s55, s55, 0x100
	s_addc_u32 s56, s56, 0
	s_cmp_gt_u32 s57, 29
	s_cbranch_scc0 .LBB0_211
	s_and_b64 vcc, exec, s[16:17]
	s_cbranch_vccz .LBB0_214
	s_barrier
